# v8 + K-loop MFMA pairs ordered n-outer m-inner (weight-side fragment held across 4 accumulator pairs)
# speedup vs baseline: 1.0091x; 1.0091x over previous
; #define PG8_STAGE(bufoff, gbase, voff) do { _Pragma("unroll") for (int _i = 0; _i < 2; ++_i) \
;         __builtin_amdgcn_global_load_lds((const unsigned*)((const char*)(gbase) + (voff)[_i]), (PG8_LAS unsigned*)(lds + (bufoff) + ldsw + _i * 8192), 16, 0, 0); } while (0)
; #define PG8_LDA(dst, b, h) do { _Pragma("unroll") for (int m = 0; m < 4; ++m) _Pragma("unroll") for (int k = 0; k < 2; ++k) dst[m][k] = *(const PG8_LAS bf16x8*)(lds + PG8_SA(b, h) + aoff + m * 2048 + k * 1024); } while (0)
; #define PG8_LDB(dst, b, h) do { _Pragma("unroll") for (int n = 0; n < 2; ++n) _Pragma("unroll") for (int k = 0; k < 2; ++k) dst[n][k] = *(const PG8_LAS bf16x8*)(lds + PG8_SB(b, h) + boff + n * 2048 + k * 1024); } while (0)
; #define PG8_MMA(ai, bj, At, Bt) do { __builtin_amdgcn_s_setprio(1); _Pragma("unroll") for (int m = 0; m < 4; ++m) _Pragma("unroll") for (int n = 0; n < 2; ++n) _Pragma("unroll") for (int k = 0; k < 2; ++k) \
;         acc[ai][bj][m][n] = __builtin_amdgcn_mfma_f32_16x16x32_bf16(Bt[n][k], At[m][k], acc[ai][bj][m][n], 0, 0, 0); __builtin_amdgcn_s_setprio(0); } while (0)
; #define PG8_WAIT_V(n) asm volatile("s_waitcnt vmcnt(" #n ")" ::: "memory")
; #define PG8_WAIT_L(n) asm volatile("s_waitcnt lgkmcnt(" #n ")" ::: "memory")
; #define PG8_BAR __builtin_amdgcn_s_barrier()
; #define PG8_SCHED __builtin_amdgcn_sched_barrier(0)
; template <class Epi, class Sched, bool ALIGN_EPI = false, bool SP2 = false>
; __device__ __forceinline__ void gemm_phase(PG8_LAS unsigned char* lds, const Gemm g, const Sched& S, const Epi& E, const int tid) {
;     ...
;             PG8_LDB(B0, 0, 0); PG8_LDB(B1, 0, 1); PG8_SCHED; PG8_LDA(At, 0, 0); PG8_STAGE(PG8_SA(1, 1), a1 + hstep, voffA);
;             PG8_WAIT_V(8); PG8_WAIT_L(0); PG8_BAR; PG8_MMA(0, 0, At, B0); PG8_MMA(0, 1, At, B1); PG8_BAR; PG8_SCHED;
;             PG8_LDA(At, 0, 1); PG8_STAGE(PG8_SB(0, 0), b2, voffB); PG8_STAGE(PG8_SB(0, 1), b2 + hstep, voffB); PG8_STAGE(PG8_SA(0, 0), a2, voffA);
;             PG8_WAIT_V(8); PG8_WAIT_L(0); PG8_BAR; PG8_MMA(1, 0, At, B0); PG8_MMA(1, 1, At, B1); PG8_BAR; PG8_SCHED;
.LBB0_209:
	s_add_i32 s69, s10, 2
	s_add_u32 s74, s0, 0x80
	s_addc_u32 s11, s1, 0
	s_add_i32 s81, 0, 0x10000
	s_cmp_eq_u32 s39, s10
	s_cselect_b32 s11, s31, s11
	s_cselect_b32 s10, s30, s74
	s_cselect_b32 s77, s35, s13
	s_cselect_b32 s76, s34, s12
	s_add_i32 s74, 0, 0x14000
	v_add_u32_e32 v142, s81, v180
	v_add_u32_e32 v168, s74, v180
	s_waitcnt lgkmcnt(0)
	ds_read_b128 v[130:133], v142
	ds_read_b128 v[134:137], v142 offset:1024
	ds_read_b128 v[138:141], v142 offset:2048
	ds_read_b128 v[142:145], v142 offset:3072
	ds_read_b128 v[164:167], v168
	ds_read_b128 v[184:187], v168 offset:1024
	ds_read_b128 v[188:191], v168 offset:2048
	ds_read_b128 v[200:203], v168 offset:3072
	v_lshl_add_u64 v[168:169], s[0:1], 0, v[160:161]
	s_add_i32 m0, s78, 0xc000
	ds_read_b128 v[204:207], v181
	ds_read_b128 v[208:211], v181 offset:1024
	ds_read_b128 v[212:215], v181 offset:2048
	ds_read_b128 v[216:219], v181 offset:3072
	ds_read_b128 v[220:223], v181 offset:4096
	ds_read_b128 v[226:229], v181 offset:5120
	ds_read_b128 v[238:241], v181 offset:6144
	ds_read_b128 v[242:245], v181 offset:7168
	global_load_lds_dwordx4 v[168:169], off
	v_lshl_add_u64 v[168:169], s[0:1], 0, v[162:163]
	s_add_i32 m0, s78, 0xe000
	s_nop 0
	global_load_lds_dwordx4 v[168:169], off
	s_waitcnt vmcnt(8)
	s_waitcnt lgkmcnt(0)
	s_barrier
	s_setprio 1
	s_waitcnt lgkmcnt(0)
	v_mfma_f32_16x16x32_bf16 v[126:129], v[130:133], v[204:207], v[126:129]
	v_mfma_f32_16x16x32_bf16 v[126:129], v[134:137], v[208:211], v[126:129]
	v_mfma_f32_16x16x32_bf16 v[110:113], v[130:133], v[212:215], v[110:113]
	v_mfma_f32_16x16x32_bf16 v[110:113], v[134:137], v[216:219], v[110:113]
	v_mfma_f32_16x16x32_bf16 v[94:97], v[130:133], v[220:223], v[94:97]
	v_mfma_f32_16x16x32_bf16 v[94:97], v[134:137], v[226:229], v[94:97]
	v_mfma_f32_16x16x32_bf16 v[78:81], v[130:133], v[238:241], v[78:81]
	v_mfma_f32_16x16x32_bf16 v[78:81], v[134:137], v[242:245], v[78:81]
	v_mfma_f32_16x16x32_bf16 v[122:125], v[138:141], v[204:207], v[122:125]
	v_mfma_f32_16x16x32_bf16 v[122:125], v[142:145], v[208:211], v[122:125]
	v_mfma_f32_16x16x32_bf16 v[106:109], v[138:141], v[212:215], v[106:109]
	v_mfma_f32_16x16x32_bf16 v[106:109], v[142:145], v[216:219], v[106:109]
	v_mfma_f32_16x16x32_bf16 v[90:93], v[138:141], v[220:223], v[90:93]
	v_mfma_f32_16x16x32_bf16 v[90:93], v[142:145], v[226:229], v[90:93]
	v_mfma_f32_16x16x32_bf16 v[74:77], v[138:141], v[238:241], v[74:77]
	v_mfma_f32_16x16x32_bf16 v[74:77], v[142:145], v[242:245], v[74:77]
	s_setprio 0
	s_setprio 1
	v_mfma_f32_16x16x32_bf16 v[118:121], v[164:167], v[204:207], v[118:121]
	v_mfma_f32_16x16x32_bf16 v[118:121], v[184:187], v[208:211], v[118:121]
	v_mfma_f32_16x16x32_bf16 v[102:105], v[164:167], v[212:215], v[102:105]
	v_mfma_f32_16x16x32_bf16 v[102:105], v[184:187], v[216:219], v[102:105]
	v_mfma_f32_16x16x32_bf16 v[86:89], v[164:167], v[220:223], v[86:89]
	v_mfma_f32_16x16x32_bf16 v[86:89], v[184:187], v[226:229], v[86:89]
	v_mfma_f32_16x16x32_bf16 v[70:73], v[164:167], v[238:241], v[70:73]
	v_mfma_f32_16x16x32_bf16 v[70:73], v[184:187], v[242:245], v[70:73]
	v_mfma_f32_16x16x32_bf16 v[114:117], v[188:191], v[204:207], v[114:117]
	v_mfma_f32_16x16x32_bf16 v[114:117], v[200:203], v[208:211], v[114:117]
	v_mfma_f32_16x16x32_bf16 v[98:101], v[188:191], v[212:215], v[98:101]
	v_mfma_f32_16x16x32_bf16 v[98:101], v[200:203], v[216:219], v[98:101]
	v_mfma_f32_16x16x32_bf16 v[82:85], v[188:191], v[220:223], v[82:85]
	v_mfma_f32_16x16x32_bf16 v[82:85], v[200:203], v[226:229], v[82:85]
	v_mfma_f32_16x16x32_bf16 v[66:69], v[188:191], v[238:241], v[66:69]
	v_mfma_f32_16x16x32_bf16 v[66:69], v[200:203], v[242:245], v[66:69]
	s_setprio 0
	s_barrier
	s_add_i32 s81, s81, s75
	v_lshl_add_u64 v[168:169], s[76:77], 0, v[148:149]
	s_mov_b32 m0, s81
	ds_read_b128 v[204:207], v181 offset:16384
	ds_read_b128 v[208:211], v181 offset:17408
	ds_read_b128 v[212:215], v181 offset:18432
	ds_read_b128 v[216:219], v181 offset:19456
	ds_read_b128 v[220:223], v181 offset:20480
	ds_read_b128 v[226:229], v181 offset:21504
	ds_read_b128 v[238:241], v181 offset:22528
	ds_read_b128 v[242:245], v181 offset:23552
	global_load_lds_dwordx4 v[168:169], off
	s_add_i32 m0, s81, 0x2000
	v_lshl_add_u64 v[246:247], s[76:77], 0, v[152:153]
	s_add_u32 s76, s76, s82
	s_addc_u32 s77, s77, 0
	s_add_i32 s74, s74, s75
	global_load_lds_dwordx4 v[246:247], off
	v_lshl_add_u64 v[248:249], s[76:77], 0, v[148:149]
	s_mov_b32 m0, s74
	v_lshl_add_u64 v[250:251], s[76:77], 0, v[152:153]
	global_load_lds_dwordx4 v[248:249], off
	s_add_i32 m0, s74, 0x2000
	v_lshl_add_u64 v[252:253], s[10:11], 0, v[146:147]
	global_load_lds_dwordx4 v[250:251], off
	s_mov_b32 m0, s78
	v_lshl_add_u64 v[194:195], s[10:11], 0, v[150:151]
	global_load_lds_dwordx4 v[252:253], off
	s_mov_b32 m0, s79
	s_nop 0
	global_load_lds_dwordx4 v[194:195], off
	s_waitcnt vmcnt(8)
	s_waitcnt lgkmcnt(0)
	s_barrier
; #define PG8_STAGE(bufoff, gbase, voff) do { _Pragma("unroll") for (int _i = 0; _i < 2; ++_i) \
;         __builtin_amdgcn_global_load_lds((const unsigned*)((const char*)(gbase) + (voff)[_i]), (PG8_LAS unsigned*)(lds + (bufoff) + ldsw + _i * 8192), 16, 0, 0); } while (0)
; #define PG8_LDA(dst, b, h) do { _Pragma("unroll") for (int m = 0; m < 4; ++m) _Pragma("unroll") for (int k = 0; k < 2; ++k) dst[m][k] = *(const PG8_LAS bf16x8*)(lds + PG8_SA(b, h) + aoff + m * 2048 + k * 1024); } while (0)
; #define PG8_LDB(dst, b, h) do { _Pragma("unroll") for (int n = 0; n < 2; ++n) _Pragma("unroll") for (int k = 0; k < 2; ++k) dst[n][k] = *(const PG8_LAS bf16x8*)(lds + PG8_SB(b, h) + boff + n * 2048 + k * 1024); } while (0)
; #define PG8_MMA(ai, bj, At, Bt) do { __builtin_amdgcn_s_setprio(1); _Pragma("unroll") for (int m = 0; m < 4; ++m) _Pragma("unroll") for (int n = 0; n < 2; ++n) _Pragma("unroll") for (int k = 0; k < 2; ++k) \
;         acc[ai][bj][m][n] = __builtin_amdgcn_mfma_f32_16x16x32_bf16(Bt[n][k], At[m][k], acc[ai][bj][m][n], 0, 0, 0); __builtin_amdgcn_s_setprio(0); } while (0)
; #define PG8_WAIT_V(n) asm volatile("s_waitcnt vmcnt(" #n ")" ::: "memory")
; #define PG8_WAIT_L(n) asm volatile("s_waitcnt lgkmcnt(" #n ")" ::: "memory")
; #define PG8_BAR __builtin_amdgcn_s_barrier()
; #define PG8_SCHED __builtin_amdgcn_sched_barrier(0)
; template <class Epi, class Sched, bool ALIGN_EPI = false, bool SP2 = false>
; __device__ __forceinline__ void gemm_phase(PG8_LAS unsigned char* lds, const Gemm g, const Sched& S, const Epi& E, const int tid) {
;     ...
;             PG8_WAIT_V(8); PG8_WAIT_L(0); PG8_BAR; PG8_MMA(1, 0, At, B0); PG8_MMA(1, 1, At, B1); PG8_BAR; PG8_SCHED;
;             PG8_LDB(B0, 1, 0); PG8_LDB(B1, 1, 1); PG8_SCHED; PG8_LDA(At, 1, 0); PG8_STAGE(PG8_SA(0, 1), a2 + hstep, voffA);
;             PG8_WAIT_V(8); PG8_WAIT_L(0); PG8_BAR; PG8_MMA(0, 0, At, B0); PG8_MMA(0, 1, At, B1); PG8_BAR; PG8_SCHED;
	s_setprio 1
	s_waitcnt lgkmcnt(0)
	v_mfma_f32_16x16x32_bf16 v[62:65], v[130:133], v[204:207], v[62:65]
	v_mfma_f32_16x16x32_bf16 v[62:65], v[134:137], v[208:211], v[62:65]
	v_mfma_f32_16x16x32_bf16 v[46:49], v[130:133], v[212:215], v[46:49]
	v_mfma_f32_16x16x32_bf16 v[46:49], v[134:137], v[216:219], v[46:49]
	v_mfma_f32_16x16x32_bf16 v[30:33], v[130:133], v[220:223], v[30:33]
	v_mfma_f32_16x16x32_bf16 v[30:33], v[134:137], v[226:229], v[30:33]
	v_mfma_f32_16x16x32_bf16 v[14:17], v[130:133], v[238:241], v[14:17]
	v_mfma_f32_16x16x32_bf16 v[14:17], v[134:137], v[242:245], v[14:17]
	v_mfma_f32_16x16x32_bf16 v[58:61], v[138:141], v[204:207], v[58:61]
	v_mfma_f32_16x16x32_bf16 v[58:61], v[142:145], v[208:211], v[58:61]
	v_mfma_f32_16x16x32_bf16 v[42:45], v[138:141], v[212:215], v[42:45]
	v_mfma_f32_16x16x32_bf16 v[42:45], v[142:145], v[216:219], v[42:45]
	v_mfma_f32_16x16x32_bf16 v[26:29], v[138:141], v[220:223], v[26:29]
	v_mfma_f32_16x16x32_bf16 v[26:29], v[142:145], v[226:229], v[26:29]
	v_mfma_f32_16x16x32_bf16 v[10:13], v[138:141], v[238:241], v[10:13]
	v_mfma_f32_16x16x32_bf16 v[10:13], v[142:145], v[242:245], v[10:13]
	s_setprio 0
	s_setprio 1
	v_mfma_f32_16x16x32_bf16 v[54:57], v[164:167], v[204:207], v[54:57]
	v_mfma_f32_16x16x32_bf16 v[54:57], v[184:187], v[208:211], v[54:57]
	v_mfma_f32_16x16x32_bf16 v[38:41], v[164:167], v[212:215], v[38:41]
	v_mfma_f32_16x16x32_bf16 v[38:41], v[184:187], v[216:219], v[38:41]
	v_mfma_f32_16x16x32_bf16 v[22:25], v[164:167], v[220:223], v[22:25]
	v_mfma_f32_16x16x32_bf16 v[22:25], v[184:187], v[226:229], v[22:25]
	v_mfma_f32_16x16x32_bf16 v[6:9], v[164:167], v[238:241], v[6:9]
	v_mfma_f32_16x16x32_bf16 v[6:9], v[184:187], v[242:245], v[6:9]
	v_mfma_f32_16x16x32_bf16 v[50:53], v[188:191], v[204:207], v[50:53]
	v_mfma_f32_16x16x32_bf16 v[50:53], v[200:203], v[208:211], v[50:53]
	v_mfma_f32_16x16x32_bf16 v[34:37], v[188:191], v[212:215], v[34:37]
	v_mfma_f32_16x16x32_bf16 v[34:37], v[200:203], v[216:219], v[34:37]
	v_mfma_f32_16x16x32_bf16 v[18:21], v[188:191], v[220:223], v[18:21]
	v_mfma_f32_16x16x32_bf16 v[18:21], v[200:203], v[226:229], v[18:21]
	v_mfma_f32_16x16x32_bf16 v[2:5], v[188:191], v[238:241], v[2:5]
	v_mfma_f32_16x16x32_bf16 v[2:5], v[200:203], v[242:245], v[2:5]
	s_setprio 0
	s_barrier
	s_add_i32 s74, 0, 0x18000
	s_add_i32 s76, 0, 0x1c000
	v_add_u32_e32 v142, s74, v180
	v_add_u32_e32 v183, s76, v180
	ds_read_b128 v[130:133], v142
	ds_read_b128 v[134:137], v142 offset:1024
	ds_read_b128 v[138:141], v142 offset:2048
	ds_read_b128 v[142:145], v142 offset:3072
	ds_read_b128 v[164:167], v183
	ds_read_b128 v[184:187], v183 offset:1024
	ds_read_b128 v[188:191], v183 offset:2048
	ds_read_b128 v[200:203], v183 offset:3072
	s_add_u32 s10, s10, s82
	s_addc_u32 s11, s11, 0
	s_mov_b32 m0, s36
	v_lshl_add_u64 v[198:199], s[10:11], 0, v[146:147]
	ds_read_b128 v[204:207], v181 offset:32768
	ds_read_b128 v[208:211], v181 offset:33792
	ds_read_b128 v[212:215], v181 offset:34816
	ds_read_b128 v[216:219], v181 offset:35840
	ds_read_b128 v[220:223], v181 offset:36864
	ds_read_b128 v[226:229], v181 offset:37888
	ds_read_b128 v[238:241], v181 offset:38912
	ds_read_b128 v[242:245], v181 offset:39936
	global_load_lds_dwordx4 v[198:199], off
	v_lshl_add_u64 v[198:199], s[10:11], 0, v[150:151]
	s_mov_b32 m0, s37
	s_nop 0
	global_load_lds_dwordx4 v[198:199], off
	s_waitcnt vmcnt(8)
	s_waitcnt lgkmcnt(0)
	s_barrier
	s_setprio 1
	s_waitcnt lgkmcnt(0)
	v_mfma_f32_16x16x32_bf16 v[126:129], v[130:133], v[204:207], v[126:129]
	v_mfma_f32_16x16x32_bf16 v[126:129], v[134:137], v[208:211], v[126:129]
	v_mfma_f32_16x16x32_bf16 v[110:113], v[130:133], v[212:215], v[110:113]
	v_mfma_f32_16x16x32_bf16 v[110:113], v[134:137], v[216:219], v[110:113]
	v_mfma_f32_16x16x32_bf16 v[94:97], v[130:133], v[220:223], v[94:97]
	v_mfma_f32_16x16x32_bf16 v[94:97], v[134:137], v[226:229], v[94:97]
	v_mfma_f32_16x16x32_bf16 v[78:81], v[130:133], v[238:241], v[78:81]
	v_mfma_f32_16x16x32_bf16 v[78:81], v[134:137], v[242:245], v[78:81]
	v_mfma_f32_16x16x32_bf16 v[122:125], v[138:141], v[204:207], v[122:125]
	v_mfma_f32_16x16x32_bf16 v[122:125], v[142:145], v[208:211], v[122:125]
	v_mfma_f32_16x16x32_bf16 v[106:109], v[138:141], v[212:215], v[106:109]
	v_mfma_f32_16x16x32_bf16 v[106:109], v[142:145], v[216:219], v[106:109]
	v_mfma_f32_16x16x32_bf16 v[90:93], v[138:141], v[220:223], v[90:93]
	v_mfma_f32_16x16x32_bf16 v[90:93], v[142:145], v[226:229], v[90:93]
	v_mfma_f32_16x16x32_bf16 v[74:77], v[138:141], v[238:241], v[74:77]
	v_mfma_f32_16x16x32_bf16 v[74:77], v[142:145], v[242:245], v[74:77]
	s_setprio 0
	s_setprio 1
	v_mfma_f32_16x16x32_bf16 v[118:121], v[164:167], v[204:207], v[118:121]
	v_mfma_f32_16x16x32_bf16 v[118:121], v[184:187], v[208:211], v[118:121]
	v_mfma_f32_16x16x32_bf16 v[102:105], v[164:167], v[212:215], v[102:105]
	v_mfma_f32_16x16x32_bf16 v[102:105], v[184:187], v[216:219], v[102:105]
	v_mfma_f32_16x16x32_bf16 v[86:89], v[164:167], v[220:223], v[86:89]
	v_mfma_f32_16x16x32_bf16 v[86:89], v[184:187], v[226:229], v[86:89]
	v_mfma_f32_16x16x32_bf16 v[70:73], v[164:167], v[238:241], v[70:73]
	v_mfma_f32_16x16x32_bf16 v[70:73], v[184:187], v[242:245], v[70:73]
	v_mfma_f32_16x16x32_bf16 v[114:117], v[188:191], v[204:207], v[114:117]
	v_mfma_f32_16x16x32_bf16 v[114:117], v[200:203], v[208:211], v[114:117]
	v_mfma_f32_16x16x32_bf16 v[98:101], v[188:191], v[212:215], v[98:101]
	v_mfma_f32_16x16x32_bf16 v[98:101], v[200:203], v[216:219], v[98:101]
	v_mfma_f32_16x16x32_bf16 v[82:85], v[188:191], v[220:223], v[82:85]
	v_mfma_f32_16x16x32_bf16 v[82:85], v[200:203], v[226:229], v[82:85]
	v_mfma_f32_16x16x32_bf16 v[66:69], v[188:191], v[238:241], v[66:69]
	v_mfma_f32_16x16x32_bf16 v[66:69], v[200:203], v[242:245], v[66:69]
	s_setprio 0
	s_barrier
; #define PG8_STAGE(bufoff, gbase, voff) do { _Pragma("unroll") for (int _i = 0; _i < 2; ++_i) \
;         __builtin_amdgcn_global_load_lds((const unsigned*)((const char*)(gbase) + (voff)[_i]), (PG8_LAS unsigned*)(lds + (bufoff) + ldsw + _i * 8192), 16, 0, 0); } while (0)
; #define PG8_LDA(dst, b, h) do { _Pragma("unroll") for (int m = 0; m < 4; ++m) _Pragma("unroll") for (int k = 0; k < 2; ++k) dst[m][k] = *(const PG8_LAS bf16x8*)(lds + PG8_SA(b, h) + aoff + m * 2048 + k * 1024); } while (0)
; #define PG8_MMA(ai, bj, At, Bt) do { __builtin_amdgcn_s_setprio(1); _Pragma("unroll") for (int m = 0; m < 4; ++m) _Pragma("unroll") for (int n = 0; n < 2; ++n) _Pragma("unroll") for (int k = 0; k < 2; ++k) \
;         acc[ai][bj][m][n] = __builtin_amdgcn_mfma_f32_16x16x32_bf16(Bt[n][k], At[m][k], acc[ai][bj][m][n], 0, 0, 0); __builtin_amdgcn_s_setprio(0); } while (0)
; #define PG8_WAIT_V(n) asm volatile("s_waitcnt vmcnt(" #n ")" ::: "memory")
; #define PG8_WAIT_L(n) asm volatile("s_waitcnt lgkmcnt(" #n ")" ::: "memory")
; #define PG8_BAR __builtin_amdgcn_s_barrier()
; #define PG8_SCHED __builtin_amdgcn_sched_barrier(0)
; template <class Epi, class Sched, bool ALIGN_EPI = false, bool SP2 = false>
; __device__ __forceinline__ void gemm_phase(PG8_LAS unsigned char* lds, const Gemm g, const Sched& S, const Epi& E, const int tid) {
;     ...
;         for (int t = 0; t < nt; t += 2) {
;             const bool last = (t == nt - 2);
;             const char* a1 = cA + (size_t)(t + 1) * kstep;
;             const char* a2 = last ? nA : cA + (size_t)(t + 2) * kstep; const char* b2 = last ? nB : cB + (size_t)(t + 2) * kstep;
;             const char* a3 = a2 + kstep; const char* b3 = b2 + kstep;
;     ...
;             PG8_LDA(At, 1, 1); PG8_STAGE(PG8_SB(1, 0), b3, voffB); PG8_STAGE(PG8_SB(1, 1), b3 + hstep, voffB); PG8_STAGE(PG8_SA(1, 0), a3, voffA);
;             PG8_WAIT_V(8); PG8_WAIT_L(0); PG8_BAR; PG8_MMA(1, 0, At, B0); PG8_MMA(1, 1, At, B1); PG8_BAR; PG8_SCHED;
;     ...
;         if constexpr (ALIGN_EPI) { if (wr == 0) PG8_BAR; }
;         if constexpr (!Epi::AFTER_DRAIN) { E(acc, cur, wr, wc, fr, fq); S.done(cur); }
	s_add_i32 s10, s74, s75
	v_lshl_add_u64 v[168:169], v[168:169], 0, s[90:91]
	s_mov_b32 m0, s10
	ds_read_b128 v[204:207], v181 offset:49152
	ds_read_b128 v[208:211], v181 offset:50176
	ds_read_b128 v[212:215], v181 offset:51200
	ds_read_b128 v[216:219], v181 offset:52224
	ds_read_b128 v[220:223], v181 offset:53248
	ds_read_b128 v[226:229], v181 offset:54272
	ds_read_b128 v[238:241], v181 offset:55296
	ds_read_b128 v[242:245], v181 offset:56320
	global_load_lds_dwordx4 v[168:169], off
	v_lshl_add_u64 v[168:169], v[246:247], 0, s[90:91]
	s_add_i32 m0, s10, 0x2000
	s_add_i32 s10, s76, s75
	global_load_lds_dwordx4 v[168:169], off
	v_lshl_add_u64 v[168:169], v[248:249], 0, s[90:91]
	s_mov_b32 m0, s10
	s_nop 0
	global_load_lds_dwordx4 v[168:169], off
	v_lshl_add_u64 v[168:169], v[250:251], 0, s[90:91]
	s_add_i32 m0, s10, 0x2000
	s_nop 0
	global_load_lds_dwordx4 v[168:169], off
	v_lshl_add_u64 v[168:169], v[252:253], 0, s[90:91]
	s_mov_b32 m0, s40
	s_nop 0
	global_load_lds_dwordx4 v[168:169], off
	v_lshl_add_u64 v[168:169], v[194:195], 0, s[90:91]
	s_mov_b32 m0, s41
	s_nop 0
	global_load_lds_dwordx4 v[168:169], off
	s_waitcnt vmcnt(8)
	s_waitcnt lgkmcnt(0)
	s_barrier
	s_setprio 1
	s_waitcnt lgkmcnt(0)
	v_mfma_f32_16x16x32_bf16 v[62:65], v[130:133], v[204:207], v[62:65]
	v_mfma_f32_16x16x32_bf16 v[62:65], v[134:137], v[208:211], v[62:65]
	v_mfma_f32_16x16x32_bf16 v[46:49], v[130:133], v[212:215], v[46:49]
	v_mfma_f32_16x16x32_bf16 v[46:49], v[134:137], v[216:219], v[46:49]
	v_mfma_f32_16x16x32_bf16 v[30:33], v[130:133], v[220:223], v[30:33]
	v_mfma_f32_16x16x32_bf16 v[30:33], v[134:137], v[226:229], v[30:33]
	v_mfma_f32_16x16x32_bf16 v[14:17], v[130:133], v[238:241], v[14:17]
	v_mfma_f32_16x16x32_bf16 v[14:17], v[134:137], v[242:245], v[14:17]
	v_mfma_f32_16x16x32_bf16 v[58:61], v[138:141], v[204:207], v[58:61]
	v_mfma_f32_16x16x32_bf16 v[58:61], v[142:145], v[208:211], v[58:61]
	v_mfma_f32_16x16x32_bf16 v[42:45], v[138:141], v[212:215], v[42:45]
	v_mfma_f32_16x16x32_bf16 v[42:45], v[142:145], v[216:219], v[42:45]
	v_mfma_f32_16x16x32_bf16 v[26:29], v[138:141], v[220:223], v[26:29]
	v_mfma_f32_16x16x32_bf16 v[26:29], v[142:145], v[226:229], v[26:29]
	v_mfma_f32_16x16x32_bf16 v[10:13], v[138:141], v[238:241], v[10:13]
	v_mfma_f32_16x16x32_bf16 v[10:13], v[142:145], v[242:245], v[10:13]
	s_setprio 0
	s_setprio 1
	v_mfma_f32_16x16x32_bf16 v[54:57], v[164:167], v[204:207], v[54:57]
	v_mfma_f32_16x16x32_bf16 v[54:57], v[184:187], v[208:211], v[54:57]
	v_mfma_f32_16x16x32_bf16 v[38:41], v[164:167], v[212:215], v[38:41]
	v_mfma_f32_16x16x32_bf16 v[38:41], v[184:187], v[216:219], v[38:41]
	v_mfma_f32_16x16x32_bf16 v[22:25], v[164:167], v[220:223], v[22:25]
	v_mfma_f32_16x16x32_bf16 v[22:25], v[184:187], v[226:229], v[22:25]
	v_mfma_f32_16x16x32_bf16 v[6:9], v[164:167], v[238:241], v[6:9]
	v_mfma_f32_16x16x32_bf16 v[6:9], v[184:187], v[242:245], v[6:9]
	v_mfma_f32_16x16x32_bf16 v[50:53], v[188:191], v[204:207], v[50:53]
	v_mfma_f32_16x16x32_bf16 v[50:53], v[200:203], v[208:211], v[50:53]
	v_mfma_f32_16x16x32_bf16 v[34:37], v[188:191], v[212:215], v[34:37]
	v_mfma_f32_16x16x32_bf16 v[34:37], v[200:203], v[216:219], v[34:37]
	v_mfma_f32_16x16x32_bf16 v[18:21], v[188:191], v[220:223], v[18:21]
	v_mfma_f32_16x16x32_bf16 v[18:21], v[200:203], v[226:229], v[18:21]
	v_mfma_f32_16x16x32_bf16 v[2:5], v[188:191], v[238:241], v[2:5]
	v_mfma_f32_16x16x32_bf16 v[2:5], v[200:203], v[242:245], v[2:5]
	s_setprio 0
	s_barrier
	s_add_u32 s0, s0, 0x100
	s_addc_u32 s1, s1, 0
	s_add_u32 s12, s12, 0x100
	s_addc_u32 s13, s13, 0
	s_cmp_ge_u32 s69, s84
	s_mov_b32 s10, s69
	s_cbranch_scc0 .LBB0_209
	s_and_b64 vcc, exec, s[22:23]
	s_cbranch_vccz .LBB0_213
	s_barrier
	s_cmp_lt_i32 s3, 3
	s_mov_b64 s[0:1], -1
	s_cbranch_scc0 .LBB0_214
